# RWKV inner loop DPP chains interleaved + HGRN hi-broadcast via op_sel (no v_mov)
# speedup vs baseline: 1.0084x; 1.0084x over previous
; #define HG_LOAD(o, t_) do { const LAS float* ob = co + ((t_) * 4 + wave) * 12; (o).F = *(const LAS f32x4*)ob; (o).K = *(const LAS f32x4*)(ob + 4); (o).Q = *(const LAS f32x4*)(ob + 8); \
;         (o).v0 = cv[(t_) * 128 + lane]; (o).v1 = cv[(t_) * 128 + 64 + lane]; asm volatile("" ::: "memory"); } while (0)
; __device__ __forceinline__ void hgrn_prompt_job3(LAS unsigned char* lds, const GAS float* Z, const GAS float* logits, int layer, int b, int h, int de, GAS bf16* OPB, GAS float* Sout, int tid, int lane, int wave) {
;     ...
;             struct HgOps { f32x4 F, K, Q; float v0, v1; };
;     ...
;             HgOps hA, hB;
;             HG_LOAD(hA, 0);
; #pragma unroll 2
;             for (int t = 0; t < 16; t += 2) { HG_LOAD(hB, t + 1); HG_STEP(hA, t); if (t + 2 < 16) HG_LOAD(hA, t + 2); HG_STEP(hB, t + 1); }
.LBB0_684:
	s_waitcnt lgkmcnt(1)
	v_pk_mul_f32 v[60:61], v[30:31], v[62:63] op_sel_hi:[0,1]
	v_pk_mul_f32 v[30:31], v[30:31], v[62:63] op_sel:[1,0]
	v_pk_fma_f32 v[60:61], v[26:27], v[58:59], v[60:61] op_sel_hi:[0,1,1]
	v_pk_fma_f32 v[30:31], v[26:27], v[64:65], v[30:31] op_sel:[1,0,0]
	v_pk_mul_f32 v[26:27], v[32:33], v[62:63] op_sel_hi:[0,1]
	v_pk_mul_f32 v[32:33], v[32:33], v[62:63] op_sel:[1,0]
	v_pk_fma_f32 v[58:59], v[28:29], v[66:67], v[26:27] op_sel_hi:[0,1,1]
	v_pk_fma_f32 v[26:27], v[28:29], v[68:69], v[32:33] op_sel:[1,0,0]
	v_pk_mul_f32 v[28:29], v[22:23], v[30:31] op_sel:[1,0]
	v_add_u32_e32 v16, 0x800, v16
	v_pk_fma_f32 v[22:23], v[22:23], v[60:61], v[28:29] op_sel_hi:[0,1,1]
	v_pk_mul_f32 v[28:29], v[24:25], v[26:27] op_sel:[1,0]
	v_pk_fma_f32 v[24:25], v[24:25], v[58:59], v[28:29] op_sel_hi:[0,1,1]
	v_pk_add_f32 v[22:23], v[22:23], v[24:25]
	ds_write2st64_b32 v109, v22, v23 offset0:24 offset1:25
	v_add_u32_e32 v109, 0x2000, v109
	v_add_u32_e32 v110, 0x300, v110
	s_andn2_b64 vcc, exec, s[0:1]
	s_add_i32 s40, s40, 4
	s_cbranch_vccz .LBB0_687
.LBB0_685:
	ds_read_b128 v[22:25], v110
	ds_read_b128 v[62:65], v110 offset:16
	ds_read_b128 v[66:69], v110 offset:32
	ds_read2st64_b32 v[28:29], v16 offset1:1
	s_waitcnt lgkmcnt(7)
	v_pk_mul_f32 v[32:33], v[12:13], v[60:61] op_sel_hi:[0,1]
	v_pk_mul_f32 v[12:13], v[12:13], v[30:31] op_sel:[1,0]
	s_waitcnt lgkmcnt(4)
	v_pk_fma_f32 v[32:33], v[56:57], v[18:19], v[32:33] op_sel_hi:[1,0,1]
	v_pk_fma_f32 v[30:31], v[56:57], v[18:19], v[12:13] op_sel:[0,1,0]
	v_pk_mul_f32 v[12:13], v[14:15], v[58:59] op_sel_hi:[0,1]
	v_pk_fma_f32 v[58:59], v[56:57], v[20:21], v[12:13] op_sel_hi:[1,0,1]
	v_pk_mul_f32 v[12:13], v[14:15], v[26:27] op_sel:[1,0]
	v_pk_fma_f32 v[26:27], v[56:57], v[20:21], v[12:13] op_sel:[0,1,0]
	v_pk_mul_f32 v[12:13], v[8:9], v[30:31] op_sel:[1,0]
	s_waitcnt lgkmcnt(0)
	v_pk_mul_f32 v[60:61], v[62:63], v[28:29] op_sel_hi:[0,1]
	v_pk_fma_f32 v[8:9], v[8:9], v[32:33], v[12:13] op_sel_hi:[0,1,1]
	v_pk_mul_f32 v[12:13], v[10:11], v[26:27] op_sel:[1,0]
	v_pk_fma_f32 v[60:61], v[22:23], v[32:33], v[60:61] op_sel_hi:[0,1,1]
	v_pk_mul_f32 v[32:33], v[62:63], v[28:29] op_sel:[1,0]
	v_pk_fma_f32 v[10:11], v[10:11], v[58:59], v[12:13] op_sel_hi:[0,1,1]
	v_pk_fma_f32 v[112:113], v[22:23], v[30:31], v[32:33] op_sel:[1,0,0]
	v_pk_mul_f32 v[22:23], v[64:65], v[28:29] op_sel_hi:[0,1]
	v_pk_add_f32 v[8:9], v[8:9], v[10:11]
	v_pk_fma_f32 v[114:115], v[24:25], v[58:59], v[22:23] op_sel_hi:[0,1,1]
	v_pk_mul_f32 v[22:23], v[64:65], v[28:29] op_sel:[1,0]
	ds_write2st64_b32 v109, v8, v9 offset1:1
	ds_read_b128 v[12:15], v110 offset:192
	ds_read_b128 v[18:21], v110 offset:208
	ds_read_b128 v[8:11], v110 offset:224
	ds_read2st64_b32 v[56:57], v16 offset0:2 offset1:3
	v_pk_fma_f32 v[116:117], v[24:25], v[26:27], v[22:23] op_sel:[1,0,0]
	v_pk_mul_f32 v[22:23], v[66:67], v[112:113] op_sel:[1,0]
	v_pk_mul_f32 v[24:25], v[68:69], v[116:117] op_sel:[1,0]
	v_pk_fma_f32 v[22:23], v[66:67], v[60:61], v[22:23] op_sel_hi:[0,1,1]
	v_pk_fma_f32 v[24:25], v[68:69], v[114:115], v[24:25] op_sel_hi:[0,1,1]
	v_pk_add_f32 v[22:23], v[22:23], v[24:25]
	ds_write2st64_b32 v109, v22, v23 offset0:8 offset1:9
	s_waitcnt lgkmcnt(4)
	v_pk_mul_f32 v[58:59], v[12:13], v[60:61] op_sel_hi:[0,1]
	v_pk_mul_f32 v[60:61], v[12:13], v[112:113] op_sel:[1,0]
	ds_read_b128 v[26:29], v110 offset:384
	ds_read_b128 v[30:33], v110 offset:400
	ds_read_b128 v[22:25], v110 offset:416
	ds_read2st64_b32 v[62:63], v16 offset0:4 offset1:5
	s_waitcnt lgkmcnt(5)
	v_pk_fma_f32 v[64:65], v[56:57], v[18:19], v[60:61] op_sel:[0,1,0]
	v_pk_mul_f32 v[60:61], v[14:15], v[114:115] op_sel_hi:[0,1]
	v_pk_fma_f32 v[66:67], v[56:57], v[20:21], v[60:61] op_sel_hi:[1,0,1]
	v_pk_mul_f32 v[60:61], v[14:15], v[116:117] op_sel:[1,0]
	v_pk_fma_f32 v[68:69], v[56:57], v[20:21], v[60:61] op_sel:[0,1,0]
	v_pk_fma_f32 v[58:59], v[56:57], v[18:19], v[58:59] op_sel_hi:[1,0,1]
	v_pk_mul_f32 v[60:61], v[8:9], v[64:65] op_sel:[1,0]
	v_pk_mul_f32 v[112:113], v[10:11], v[68:69] op_sel:[1,0]
	s_cmp_gt_u32 s40, 13
	v_pk_fma_f32 v[60:61], v[8:9], v[58:59], v[60:61] op_sel_hi:[0,1,1]
	v_pk_fma_f32 v[112:113], v[10:11], v[66:67], v[112:113] op_sel_hi:[0,1,1]
	s_cselect_b64 s[0:1], -1, 0
	v_pk_add_f32 v[60:61], v[60:61], v[112:113]
	s_and_b64 vcc, exec, s[0:1]
	ds_write2st64_b32 v109, v60, v61 offset0:16 offset1:17
	s_cbranch_vccnz .LBB0_684
	ds_read_b128 v[12:15], v110 offset:576
	ds_read_b128 v[18:21], v110 offset:592
	ds_read_b128 v[8:11], v110 offset:608
	ds_read2st64_b32 v[56:57], v16 offset0:6 offset1:7
	s_branch .LBB0_684

; #define LAS __attribute__((address_space(3)))
; #define R4_ISSUE(cc, slot) do { const GAS float* g_ = gp + (size_t)(cc) * 2048; LAS float* l_ = ring + (slot) * 1536; _Pragma("unroll") for (int i_ = 0; i_ < 6; ++i_) \
;         __builtin_amdgcn_global_load_lds((const GAS unsigned*)(g_ + off[i_]), (LAS unsigned*)(l_ + i_ * 256), 16, 0, 0); } while (0)
; #define R4_LOAD(o, sb_) do { const LAS float* sb = (sb_); (o).r = *(const LAS f32x4*)(sb + cgp * 4); (o).w = *(const LAS f32x4*)(sb + 64 + cgp * 4); (o).k = *(const LAS f32x4*)(sb + 128 + cgp * 4); \
;         (o).a = *(const LAS f32x4*)(sb + 256 + cgp * 4); (o).b = *(const LAS f32x4*)(sb + 320 + cgp * 4); (o).vv = sb[192 + rq * 4 + rl]; asm volatile("" ::: "memory"); } while (0)
; __device__ __forceinline__ void rwkv_prompt_wave4(LAS float* ring, const GAS float* RW, int mbase, int h, int rq, GAS float* Sout, GAS float* YR, int lane) {
;     ...
;     for (int cc = 0; cc < 3; ++cc) R4_ISSUE(cc, cc);
;     float ykeep = 0.f;
;     R4Ops oA, oB, oC, oD;
;     asm volatile("s_waitcnt vmcnt(12)" ::: "memory");
;     R4_LOAD(oA, ring); R4_LOAD(oB, ring + 384);
;     for (int ci = 0; ci < NCH; ++ci) {
;         { const int cn = ci + 3; const int cl = cn < NCH ? cn : NCH - 1; R4_ISSUE(cl, cn % R4_NS); }
;         const LAS float* cb = ring + (ci % R4_NS) * 1536; const LAS float* nb = ring + ((ci + 1) % R4_NS) * 1536;
;         R4_LOAD(oC, cb + 768);  R4_STEP(oA, 0);
;         R4_LOAD(oD, cb + 1152); R4_STEP(oB, 1);
;         asm volatile("s_waitcnt vmcnt(12)" ::: "memory");
;         R4_LOAD(oA, nb);        R4_STEP(oC, 2);
;         R4_LOAD(oB, nb + 384);  R4_STEP(oD, 3);
;         if (cgp < 4) YR[(size_t)(mbase + ci * 4 + cgp) * 512 + h * 64 + rq * 4 + rl] = ykeep;
.LBB0_707:
	s_mul_hi_u32 s0, s20, 0xcccccccd
	s_lshr_b32 s0, s0, 2
	s_mulk_i32 s0, 0x7800
	v_subrev_u32_e32 v63, s0, v70
	v_subrev_u32_e32 v109, s0, v67
	s_mul_hi_u32 s0, s21, 0xcccccccd
	s_lshr_b32 s0, s0, 2
	s_add_i32 s24, s21, 3
	s_cmpk_lt_u32 s21, 0x1fd
	s_mulk_i32 s0, 0x7800
	s_cselect_b32 s82, s18, 0xff800
	v_subrev_u32_e32 v88, s0, v70
	v_subrev_u32_e32 v74, s0, v67
	s_lshl_b64 s[0:1], s[82:83], 2
	s_add_u32 s0, s10, s0
	s_mul_i32 s25, s24, 0xcccd
	s_addc_u32 s1, s11, s1
	s_lshr_b32 s25, s25, 18
	s_mul_i32 s25, s25, 5
	s_sub_i32 s24, s24, s25
	s_and_b32 s24, s24, 0xffff
	s_mulk_i32 s24, 0x1800
	s_add_i32 s24, s14, s24
	s_mov_b32 m0, s24
	v_lshl_add_u64 v[72:73], v[46:47], 2, s[0:1]
	global_load_lds_dwordx4 v53, s[0:1]
	s_add_i32 m0, s24, 0x400
	s_waitcnt lgkmcnt(6)
	v_pk_mul_f32 v[28:29], v[44:45], v[28:29]
	global_load_lds_dwordx4 v[72:73], off
	v_lshl_add_u64 v[72:73], s[0:1], 0, v[16:17]
	v_lshl_add_u64 v[72:73], v[72:73], 0, s[52:53]
	s_add_i32 m0, s24, 0x800
	v_pk_fma_f32 v[26:27], v[42:43], v[26:27], v[28:29]
	global_load_lds_dwordx4 v[72:73], off
	s_add_i32 m0, s24, 0xc00
	v_lshl_add_u64 v[72:73], v[48:49], 2, s[0:1]
	global_load_lds_dwordx4 v69, s[0:1]
	s_add_i32 m0, s24, 0x1000
	v_add_f32_e32 v26, v26, v27
	global_load_lds_dwordx4 v[72:73], off
	v_lshl_add_u64 v[72:73], v[50:51], 2, s[0:1]
	s_add_i32 m0, s24, 0x1400
	v_add_f32_dpp v26, v26, v26 quad_perm:[1,0,3,2] row_mask:0xf bank_mask:0xf bound_ctrl:1
	global_load_lds_dwordx4 v[72:73], off
	s_nop 0
	v_add_f32_dpp v26, v26, v26 quad_perm:[2,3,0,1] row_mask:0xf bank_mask:0xf bound_ctrl:1
	s_add_i32 s0, s14, s19
	v_add_u32_e32 v104, s0, v74
	v_add_f32_dpp v26, v26, v26 row_half_mirror row_mask:0xf bank_mask:0xf bound_ctrl:1
	ds_read_b128 v[72:75], v104 offset:3072
	ds_read_b128 v[76:79], v104 offset:3328
	ds_read_b128 v[80:83], v104 offset:3584
	ds_read_b128 v[84:87], v104 offset:4096
	v_add_f32_dpp v26, v26, v26 row_mirror row_mask:0xf bank_mask:0xf bound_ctrl:1
	v_pk_mul_f32 v[22:23], v[22:23], v[26:27] op_sel_hi:[1,0]
	v_add_u32_e32 v110, s0, v88
	v_pk_fma_f32 v[8:9], v[64:65], v[8:9], v[22:23] op_sel_hi:[0,1,1]
	v_pk_fma_f32 v[4:5], v[42:43], v[4:5], v[8:9]
	v_pk_mul_f32 v[8:9], v[24:25], v[26:27] op_sel_hi:[1,0]
	ds_read_b128 v[88:91], v104 offset:4352
	ds_read_b32 v108, v110 offset:3840
	v_pk_fma_f32 v[8:9], v[64:65], v[10:11], v[8:9] op_sel_hi:[0,1,1]
	v_pk_fma_f32 v[6:7], v[44:45], v[6:7], v[8:9]
	ds_read_b128 v[92:95], v104 offset:4608
	ds_read_b128 v[42:45], v104 offset:4864
	ds_read_b128 v[96:99], v104 offset:5120
	ds_read_b128 v[100:103], v104 offset:5632
	ds_read_b128 v[104:107], v104 offset:5888
	ds_read_b32 v110, v110 offset:5376
	s_waitcnt lgkmcnt(12)
	v_pk_mul_f32 v[2:3], v[2:3], v[6:7]
	v_pk_mul_f32 v[40:41], v[40:41], v[6:7]
	s_waitcnt vmcnt(12)
	v_add_u32_e32 v63, s0, v63
	v_pk_fma_f32 v[0:1], v[0:1], v[4:5], v[2:3]
	v_pk_fma_f32 v[38:39], v[38:39], v[4:5], v[40:41]
	v_add_f32_e32 v0, v0, v1
	s_nop 0
	v_add_f32_e32 v38, v38, v39
	s_nop 0
	v_add_f32_dpp v0, v0, v0 quad_perm:[1,0,3,2] row_mask:0xf bank_mask:0xf bound_ctrl:1
	v_add_f32_dpp v38, v38, v38 quad_perm:[1,0,3,2] row_mask:0xf bank_mask:0xf bound_ctrl:1
	s_nop 0
	v_add_f32_dpp v0, v0, v0 quad_perm:[2,3,0,1] row_mask:0xf bank_mask:0xf bound_ctrl:1
	v_add_f32_dpp v38, v38, v38 quad_perm:[2,3,0,1] row_mask:0xf bank_mask:0xf bound_ctrl:1
	s_nop 0
	v_add_f32_dpp v0, v0, v0 row_half_mirror row_mask:0xf bank_mask:0xf bound_ctrl:1
	v_add_f32_dpp v38, v38, v38 row_half_mirror row_mask:0xf bank_mask:0xf bound_ctrl:1
	s_nop 0
	v_add_f32_dpp v0, v0, v0 row_mirror row_mask:0xf bank_mask:0xf bound_ctrl:1
	v_add_f32_dpp v38, v38, v38 row_mirror row_mask:0xf bank_mask:0xf bound_ctrl:1
	v_cndmask_b32_e32 v8, v71, v0, vcc
	v_pk_mul_f32 v[2:3], v[34:35], v[38:39] op_sel_hi:[1,0]
	v_pk_mul_f32 v[0:1], v[36:37], v[38:39] op_sel_hi:[1,0]
	v_pk_fma_f32 v[2:3], v[66:67], v[30:31], v[2:3] op_sel_hi:[0,1,1]
	v_pk_fma_f32 v[0:1], v[66:67], v[32:33], v[0:1] op_sel_hi:[0,1,1]
	v_pk_fma_f32 v[20:21], v[20:21], v[6:7], v[0:1]
	v_pk_fma_f32 v[18:19], v[18:19], v[4:5], v[2:3]
	v_pk_mul_f32 v[0:1], v[14:15], v[20:21]
	v_add_u32_e32 v34, s0, v109
	v_pk_fma_f32 v[0:1], v[12:13], v[18:19], v[0:1]
	s_waitcnt lgkmcnt(0)
; #define LAS __attribute__((address_space(3)))
; #define R4_ISSUE(cc, slot) do { const GAS float* g_ = gp + (size_t)(cc) * 2048; LAS float* l_ = ring + (slot) * 1536; _Pragma("unroll") for (int i_ = 0; i_ < 6; ++i_) \
;         __builtin_amdgcn_global_load_lds((const GAS unsigned*)(g_ + off[i_]), (LAS unsigned*)(l_ + i_ * 256), 16, 0, 0); } while (0)
; #define R4_LOAD(o, sb_) do { const LAS float* sb = (sb_); (o).r = *(const LAS f32x4*)(sb + cgp * 4); (o).w = *(const LAS f32x4*)(sb + 64 + cgp * 4); (o).k = *(const LAS f32x4*)(sb + 128 + cgp * 4); \
;         (o).a = *(const LAS f32x4*)(sb + 256 + cgp * 4); (o).b = *(const LAS f32x4*)(sb + 320 + cgp * 4); (o).vv = sb[192 + rq * 4 + rl]; asm volatile("" ::: "memory"); } while (0)
; __device__ __forceinline__ void rwkv_prompt_wave4(LAS float* ring, const GAS float* RW, int mbase, int h, int rq, GAS float* Sout, GAS float* YR, int lane) {
;     ...
;     for (int cc = 0; cc < 3; ++cc) R4_ISSUE(cc, cc);
;     float ykeep = 0.f;
;     R4Ops oA, oB, oC, oD;
;     asm volatile("s_waitcnt vmcnt(12)" ::: "memory");
;     R4_LOAD(oA, ring); R4_LOAD(oB, ring + 384);
;     for (int ci = 0; ci < NCH; ++ci) {
;         { const int cn = ci + 3; const int cl = cn < NCH ? cn : NCH - 1; R4_ISSUE(cl, cn % R4_NS); }
;         const LAS float* cb = ring + (ci % R4_NS) * 1536; const LAS float* nb = ring + ((ci + 1) % R4_NS) * 1536;
;         R4_LOAD(oC, cb + 768);  R4_STEP(oA, 0);
;         R4_LOAD(oD, cb + 1152); R4_STEP(oB, 1);
;         asm volatile("s_waitcnt vmcnt(12)" ::: "memory");
;         R4_LOAD(oA, nb);        R4_STEP(oC, 2);
;         R4_LOAD(oB, nb + 384);  R4_STEP(oD, 3);
;         if (cgp < 4) YR[(size_t)(mbase + ci * 4 + cgp) * 512 + h * 64 + rq * 4 + rl] = ykeep;
	v_pk_mul_f32 v[12:13], v[86:87], v[20:21]
	v_add_f32_e32 v0, v0, v1
	v_pk_fma_f32 v[12:13], v[84:85], v[18:19], v[12:13]
	s_nop 0
	v_add_f32_e32 v12, v12, v13
	v_add_f32_dpp v0, v0, v0 quad_perm:[1,0,3,2] row_mask:0xf bank_mask:0xf bound_ctrl:1
	s_nop 0
	v_add_f32_dpp v12, v12, v12 quad_perm:[1,0,3,2] row_mask:0xf bank_mask:0xf bound_ctrl:1
	v_add_f32_dpp v0, v0, v0 quad_perm:[2,3,0,1] row_mask:0xf bank_mask:0xf bound_ctrl:1
	s_nop 0
	v_add_f32_dpp v12, v12, v12 quad_perm:[2,3,0,1] row_mask:0xf bank_mask:0xf bound_ctrl:1
	v_add_f32_dpp v0, v0, v0 row_half_mirror row_mask:0xf bank_mask:0xf bound_ctrl:1
	s_nop 0
	v_add_f32_dpp v12, v12, v12 row_half_mirror row_mask:0xf bank_mask:0xf bound_ctrl:1
	v_add_f32_dpp v0, v0, v0 row_mirror row_mask:0xf bank_mask:0xf bound_ctrl:1
	v_cndmask_b32_e64 v30, v8, v0, s[4:5]
	v_add_f32_dpp v12, v12, v12 row_mirror row_mask:0xf bank_mask:0xf bound_ctrl:1
	v_pk_mul_f32 v[14:15], v[88:89], v[12:13] op_sel_hi:[1,0]
	v_pk_mul_f32 v[12:13], v[90:91], v[12:13] op_sel_hi:[1,0]
	v_pk_fma_f32 v[14:15], v[80:81], v[108:109], v[14:15] op_sel_hi:[1,0,1]
	v_pk_fma_f32 v[12:13], v[82:83], v[108:109], v[12:13] op_sel_hi:[1,0,1]
	v_pk_fma_f32 v[76:77], v[76:77], v[18:19], v[14:15]
	v_pk_fma_f32 v[78:79], v[78:79], v[20:21], v[12:13]
	ds_read_b128 v[0:3], v34 offset:6144
	v_pk_mul_f32 v[12:13], v[74:75], v[78:79]
	ds_read_b128 v[4:7], v34 offset:6400
	v_pk_fma_f32 v[12:13], v[72:73], v[76:77], v[12:13]
	ds_read_b128 v[8:11], v34 offset:6656
	v_pk_mul_f32 v[72:73], v[102:103], v[78:79]
	v_add_f32_e32 v12, v12, v13
	v_pk_fma_f32 v[72:73], v[100:101], v[76:77], v[72:73]
	ds_read_b128 v[26:29], v34 offset:7168
	v_add_f32_e32 v72, v72, v73
	ds_read_b128 v[22:25], v34 offset:7424
	v_add_f32_dpp v12, v12, v12 quad_perm:[1,0,3,2] row_mask:0xf bank_mask:0xf bound_ctrl:1
	ds_read_b32 v64, v63 offset:6912
	v_add_f32_dpp v72, v72, v72 quad_perm:[1,0,3,2] row_mask:0xf bank_mask:0xf bound_ctrl:1
	s_nop 0
	v_add_f32_dpp v12, v12, v12 quad_perm:[2,3,0,1] row_mask:0xf bank_mask:0xf bound_ctrl:1
	v_add_f32_dpp v72, v72, v72 quad_perm:[2,3,0,1] row_mask:0xf bank_mask:0xf bound_ctrl:1
	s_nop 0
	v_add_f32_dpp v12, v12, v12 row_half_mirror row_mask:0xf bank_mask:0xf bound_ctrl:1
	v_add_f32_dpp v72, v72, v72 row_half_mirror row_mask:0xf bank_mask:0xf bound_ctrl:1
	s_nop 0
	v_add_f32_dpp v12, v12, v12 row_mirror row_mask:0xf bank_mask:0xf bound_ctrl:1
	v_add_f32_dpp v72, v72, v72 row_mirror row_mask:0xf bank_mask:0xf bound_ctrl:1
	v_cndmask_b32_e64 v71, v30, v12, s[6:7]
	v_pk_mul_f32 v[74:75], v[104:105], v[72:73] op_sel_hi:[1,0]
	v_pk_mul_f32 v[72:73], v[106:107], v[72:73] op_sel_hi:[1,0]
	v_pk_fma_f32 v[74:75], v[96:97], v[110:111], v[74:75] op_sel_hi:[1,0,1]
	v_pk_fma_f32 v[72:73], v[98:99], v[110:111], v[72:73] op_sel_hi:[1,0,1]
	v_pk_fma_f32 v[42:43], v[42:43], v[76:77], v[74:75]
	v_pk_fma_f32 v[44:45], v[44:45], v[78:79], v[72:73]
	ds_read_b128 v[12:15], v34 offset:7680
	v_pk_mul_f32 v[72:73], v[94:95], v[44:45]
	ds_read_b128 v[18:21], v34 offset:7936
	v_pk_fma_f32 v[72:73], v[92:93], v[42:43], v[72:73]
	ds_read_b128 v[30:33], v34 offset:8192
	v_add_f32_e32 v72, v72, v73
	ds_read_b128 v[38:41], v34 offset:8704
	ds_read_b128 v[34:37], v34 offset:8960
	v_add_f32_dpp v72, v72, v72 quad_perm:[1,0,3,2] row_mask:0xf bank_mask:0xf bound_ctrl:1
	ds_read_b32 v66, v63 offset:8448
	s_nop 0
	v_add_f32_dpp v72, v72, v72 quad_perm:[2,3,0,1] row_mask:0xf bank_mask:0xf bound_ctrl:1
	s_nop 1
	v_add_f32_dpp v72, v72, v72 row_half_mirror row_mask:0xf bank_mask:0xf bound_ctrl:1
	s_nop 1
	v_add_f32_dpp v72, v72, v72 row_mirror row_mask:0xf bank_mask:0xf bound_ctrl:1
	v_cndmask_b32_e64 v71, v71, v72, s[8:9]
	s_and_saveexec_b64 s[0:1], s[40:41]
	s_cbranch_execz .LBB0_706
	v_ashrrev_i32_e32 v63, 31, v62
	v_lshlrev_b64 v[72:73], 11, v[62:63]
	v_lshl_add_u64 v[72:73], v[60:61], 0, v[72:73]
	global_store_dword v[72:73], v71, off
	s_branch .LBB0_706
